# v192 stack plus paired 64-bit register clears in P3 (v_mov_b64 instead of two v_mov_b32)
# baseline (speedup 1.0000x reference)
.Lp3_tap_skip:
	v_add_u32_e32 v1, s84, v0
	v_add_u32_e32 v0, 0, v0
	s_add_i32 s35, s84, s34
	v_add_u32_e32 v0, 0x1cc00, v0
	v_mov_b32_e32 v3, s35
	ds_read_b32 v31, v1
	ds_read_b32 v26, v0
	ds_read_b32 v37, v3 offset:252
	v_and_b32_e32 v27, 7, v36
	v_lshlrev_b32_e32 v30, 4, v27
	v_or_b32_e32 v2, s56, v30
	v_add_u32_e32 v6, s30, v29
	v_lshlrev_b32_e32 v196, 1, v2
	v_mov_b32_e32 v2, 0
	v_lshl_add_u32 v28, v27, 6, s86
	v_lshl_add_u64 v[0:1], s[62:63], 0, v[196:197]
	v_cmp_lt_i32_e64 s[56:57], -1, v6
	v_mov_b32_e32 v3, 0
	v_mov_b64_e32 v[14:15], 0
	v_mov_b32_e32 v20, 0
	v_mov_b32_e32 v21, v2
	v_mov_b32_e32 v16, v2
	v_mov_b32_e32 v17, v2
	v_mov_b32_e32 v18, v2
	v_mov_b32_e32 v19, v2
	v_mov_b32_e32 v8, v2
	v_mov_b32_e32 v9, v2
	v_mov_b32_e32 v10, v2
	v_mov_b32_e32 v11, v2
	v_mov_b32_e32 v12, v2
	v_mov_b32_e32 v13, v2
	v_mov_b32_e32 v22, 0
	v_mov_b32_e32 v23, 0
	s_and_saveexec_b64 s[8:9], s[56:57]
	s_cbranch_execz .LBB0_201
	v_mov_b32_e32 v7, v197
	v_lshl_add_u64 v[2:3], s[12:13], 0, v[6:7]
	v_mad_u64_u32 v[8:9], s[52:53], v2, s91, v[0:1]
	v_mad_i32_i24 v9, v3, s91, v9
	ds_read_b128 v[14:17], v28
	ds_read_b128 v[22:25], v28 offset:16
	ds_read_b128 v[42:45], v28 offset:32
	ds_read_b128 v[46:49], v28 offset:48
	v_lshlrev_b32_e32 v12, 16, v116
	v_and_b32_e32 v13, 0xffff0000, v116
	v_lshlrev_b32_e32 v8, 16, v117
	v_and_b32_e32 v9, 0xffff0000, v117
	s_waitcnt lgkmcnt(3)
	v_pk_fma_f32 v[20:21], v[16:17], v[8:9], 0 op_sel_hi:[1,1,0]
	v_lshlrev_b32_e32 v8, 16, v118
	v_and_b32_e32 v9, 0xffff0000, v118
	s_waitcnt lgkmcnt(2)
	v_pk_fma_f32 v[16:17], v[22:23], v[8:9], 0 op_sel_hi:[1,1,0]
	v_lshlrev_b32_e32 v8, 16, v119
	v_and_b32_e32 v9, 0xffff0000, v119
	v_pk_fma_f32 v[18:19], v[24:25], v[8:9], 0 op_sel_hi:[1,1,0]
	v_lshlrev_b32_e32 v8, 16, v120
	v_and_b32_e32 v9, 0xffff0000, v120
	v_lshlrev_b32_e32 v2, 16, v121
	v_and_b32_e32 v3, 0xffff0000, v121
	s_waitcnt lgkmcnt(1)
	v_pk_fma_f32 v[10:11], v[44:45], v[2:3], 0 op_sel_hi:[1,1,0]
	v_lshlrev_b32_e32 v2, 16, v122
	v_and_b32_e32 v3, 0xffff0000, v122
	v_pk_fma_f32 v[14:15], v[14:15], v[12:13], 0 op_sel_hi:[1,1,0]
	s_waitcnt lgkmcnt(0)
	v_pk_fma_f32 v[12:13], v[46:47], v[2:3], 0 op_sel_hi:[1,1,0]
	v_lshlrev_b32_e32 v2, 16, v123
	v_and_b32_e32 v3, 0xffff0000, v123
	v_pk_fma_f32 v[2:3], v[48:49], v[2:3], 0 op_sel_hi:[1,1,0]
	v_pk_fma_f32 v[8:9], v[42:43], v[8:9], 0 op_sel_hi:[1,1,0]
	v_mov_b32_e32 v22, v2
	v_mov_b32_e32 v23, v3

.LBB0_207:
	s_or_b64 exec, exec, s[8:9]
	v_mul_f32_e32 v3, 0xbfb8aa3b, v14
	v_exp_f32_e32 v3, v3
	v_mul_f32_e32 v5, 0xbfb8aa3b, v15
	v_exp_f32_e32 v5, v5
	v_mul_f32_e32 v24, 0xbfb8aa3b, v21
	v_add_f32_e32 v3, 1.0, v3
	v_rcp_f32_e32 v3, v3
	v_add_f32_e32 v5, 1.0, v5
	v_rcp_f32_e32 v5, v5
	v_mul_f32_e32 v7, 0xbfb8aa3b, v20
	v_mul_f32_e32 v3, v14, v3
	v_exp_f32_e32 v14, v24
	v_exp_f32_e32 v7, v7
	v_mul_f32_e32 v24, 0xbfb8aa3b, v16
	v_mul_f32_e32 v5, v15, v5
	v_add_f32_e32 v14, 1.0, v14
	v_mul_f32_e32 v15, 0xbfb8aa3b, v17
	v_rcp_f32_e32 v14, v14
	v_exp_f32_e32 v24, v24
	v_exp_f32_e32 v15, v15
	v_add_f32_e32 v7, 1.0, v7
	v_rcp_f32_e32 v7, v7
	v_mul_f32_e32 v25, v21, v14
	v_add_f32_e32 v14, 1.0, v24
	v_add_f32_e32 v15, 1.0, v15
	v_mul_f32_e32 v21, 0xbfb8aa3b, v19
	v_rcp_f32_e32 v14, v14
	v_rcp_f32_e32 v15, v15
	v_exp_f32_e32 v21, v21
	v_mul_f32_e32 v7, v20, v7
	v_mul_f32_e32 v20, 0xbfb8aa3b, v18
	v_exp_f32_e32 v20, v20
	v_mul_f32_e32 v24, v16, v14
	v_mul_f32_e32 v42, v17, v15
	v_add_f32_e32 v14, 1.0, v21
	v_mul_f32_e32 v15, 0xbfb8aa3b, v8
	v_mul_f32_e32 v16, 0xbfb8aa3b, v9
	v_rcp_f32_e32 v14, v14
	v_exp_f32_e32 v15, v15
	v_exp_f32_e32 v16, v16
	v_add_f32_e32 v20, 1.0, v20
	v_rcp_f32_e32 v20, v20
	v_mul_f32_e32 v48, v19, v14
	v_add_f32_e32 v14, 1.0, v15
	v_add_f32_e32 v15, 1.0, v16
	v_mul_f32_e32 v16, 0xbfb8aa3b, v10
	v_mul_f32_e32 v17, 0xbfb8aa3b, v11
	v_exp_f32_e32 v16, v16
	v_exp_f32_e32 v17, v17
	v_mul_f32_e32 v47, v18, v20
	v_mul_f32_e32 v18, 0xbfb8aa3b, v12
	v_mul_f32_e32 v19, 0xbfb8aa3b, v13
	v_mul_f32_e32 v43, v5, v5
	v_exp_f32_e32 v18, v18
	v_exp_f32_e32 v19, v19
	v_fmac_f32_e32 v43, v3, v3
	v_rcp_f32_e32 v14, v14
	v_rcp_f32_e32 v15, v15
	v_fmac_f32_e32 v43, v7, v7
	v_add_f32_e32 v16, 1.0, v16
	v_add_f32_e32 v17, 1.0, v17
	v_mul_f32_e32 v20, 0xbfb8aa3b, v22
	v_mul_f32_e32 v21, 0xbfb8aa3b, v23
	v_fmac_f32_e32 v43, v25, v25
	v_rcp_f32_e32 v16, v16
	v_rcp_f32_e32 v17, v17
	v_exp_f32_e32 v20, v20
	v_exp_f32_e32 v21, v21
	v_fmac_f32_e32 v43, v24, v24
	v_add_f32_e32 v18, 1.0, v18
	v_add_f32_e32 v19, 1.0, v19
	v_fmac_f32_e32 v43, v42, v42
	v_rcp_f32_e32 v18, v18
	v_rcp_f32_e32 v19, v19
	v_fmac_f32_e32 v43, v47, v47
	v_pk_mul_f32 v[8:9], v[8:9], v[14:15]
	v_fmac_f32_e32 v43, v48, v48
	v_pk_mul_f32 v[14:15], v[8:9], v[8:9]
	v_add_f32_e32 v20, 1.0, v20
	v_add_f32_e32 v21, 1.0, v21
	v_add_f32_e32 v14, v43, v14
	v_pk_mul_f32 v[10:11], v[10:11], v[16:17]
	v_rcp_f32_e32 v20, v20
	v_rcp_f32_e32 v21, v21
	v_add_f32_e32 v43, v14, v15
	v_pk_mul_f32 v[14:15], v[10:11], v[10:11]
	v_pk_mul_f32 v[12:13], v[12:13], v[18:19]
	v_add_f32_e32 v14, v43, v14
	v_add_f32_e32 v16, v14, v15
	v_pk_mul_f32 v[14:15], v[12:13], v[12:13]
	s_lshl_b32 s8, s31, 5
	v_add_f32_e32 v14, v16, v14
	v_add_f32_e32 v18, v14, v15
	v_pk_mul_f32 v[14:15], v[22:23], v[20:21]
	s_waitcnt lgkmcnt(2)
	v_mul_f32_e32 v23, 0x3fb8aa3b, v31
	v_pk_mul_f32 v[16:17], v[14:15], v[14:15]
	v_exp_f32_e32 v46, v23
	v_add_f32_e32 v16, v18, v16
	v_and_b32_e32 v18, 64, v227
	v_add_f32_e32 v16, v16, v17
	v_xor_b32_e32 v17, 1, v227
	v_add_u32_e32 v18, 64, v18
	v_cmp_lt_i32_e32 vcc, v17, v18
	s_add_i32 s8, s8, s29
	s_mul_i32 s76, s8, 0xf400
	v_cndmask_b32_e32 v17, v227, v17, vcc
	v_lshlrev_b32_e32 v45, 2, v17
	ds_bpermute_b32 v17, v45, v16
	v_lshl_add_u32 v20, v30, 1, 0
	v_mul_lo_u32 v21, v29, s87
	s_mul_hi_i32 s9, s8, 0xf400
	s_add_u32 s76, s81, s76
	s_waitcnt lgkmcnt(0)
	v_add_f32_e32 v16, v16, v17
	v_xor_b32_e32 v17, 2, v227
	v_cmp_lt_i32_e32 vcc, v17, v18
	s_addc_u32 s77, s75, s9
	s_movk_i32 s9, 0x88
	v_cndmask_b32_e32 v17, v227, v17, vcc
	v_lshlrev_b32_e32 v44, 2, v17
	ds_bpermute_b32 v17, v44, v16
	s_mov_b64 s[78:79], 0x4400
	s_waitcnt lgkmcnt(0)
	v_add_f32_e32 v19, v16, v17
	v_xor_b32_e32 v16, 4, v227
	v_cmp_lt_i32_e32 vcc, v16, v18
	s_nop 1
	v_cndmask_b32_e32 v16, v227, v16, vcc
	v_lshlrev_b32_e32 v43, 2, v16
	ds_bpermute_b32 v18, v43, v19
	v_mul_lo_u32 v16, v29, s9
	v_add_lshl_u32 v16, v16, v30, 1
	v_ashrrev_i32_e32 v17, 31, v16
	v_lshl_add_u64 v[16:17], s[76:77], 0, v[16:17]
	s_waitcnt lgkmcnt(0)
	v_add_f32_e32 v18, v19, v18
	v_add_f32_e32 v18, 0x358637bd, v18
	v_mul_f32_e32 v19, 0x4b800000, v18
	v_cmp_gt_f32_e32 vcc, s85, v18
	s_nop 1
	v_cndmask_b32_e32 v18, v18, v19, vcc
	v_rsq_f32_e32 v22, v18
	v_lshl_add_u64 v[18:19], v[16:17], 0, s[78:79]
	v_mul_f32_e32 v23, 0x45800000, v22
	v_cndmask_b32_e32 v22, v22, v23, vcc
	v_mul_f32_e32 v22, 0x3db504f3, v22
	v_mul_f32_e32 v5, v22, v5
	v_mul_f32_e32 v3, v22, v3
	v_mul_f32_e32 v52, v22, v11
	v_mul_f32_e32 v53, v22, v10
	v_mul_f32_e32 v54, v22, v9
	v_mul_f32_e32 v55, v22, v8
	v_mul_f32_e32 v48, v22, v48
	v_mul_f32_e32 v47, v22, v47
	v_mul_f32_e32 v56, v22, v42
	v_mul_f32_e32 v24, v22, v24
	v_mul_f32_e32 v25, v22, v25
	v_mul_f32_e32 v7, v22, v7
	v_cvt_pk_bf16_f32 v8, v3, v5
	v_cvt_pk_bf16_f32 v9, v7, v25
	v_cvt_pk_bf16_f32 v10, v24, v56
	v_cvt_pk_bf16_f32 v11, v47, v48
	v_add_u32_e32 v42, v20, v21
	v_mul_f32_e32 v3, v46, v3
	v_mul_f32_e32 v5, v46, v5
	v_mul_f32_e32 v23, v22, v15
	v_mul_f32_e32 v49, v22, v14
	v_mul_f32_e32 v50, v22, v13
	v_mul_f32_e32 v51, v22, v12
	v_cvt_pk_bf16_f32 v12, v55, v54
	v_cvt_pk_bf16_f32 v13, v53, v52
	v_cvt_pk_bf16_f32 v14, v51, v50
	v_cvt_pk_bf16_f32 v15, v49, v23
	ds_write_b128 v42, v[8:11] offset:17408
	ds_write_b128 v42, v[12:15] offset:17424
	v_cvt_pk_bf16_f32 v8, v3, v5
	v_mul_f32_e32 v3, v46, v7
	v_mul_f32_e32 v5, v46, v25
	v_cvt_pk_bf16_f32 v9, v3, v5
	v_mul_f32_e32 v3, v46, v55
	v_mul_f32_e32 v5, v46, v54
	v_cvt_pk_bf16_f32 v10, v3, v5
	v_mul_f32_e32 v3, v46, v53
	v_mul_f32_e32 v5, v46, v52
	v_cvt_pk_bf16_f32 v11, v3, v5
	v_mul_f32_e32 v3, v46, v24
	v_mul_f32_e32 v5, v46, v56
	v_cvt_pk_bf16_f32 v12, v3, v5
	v_mul_f32_e32 v3, v46, v47
	v_mul_f32_e32 v5, v46, v48
	v_cvt_pk_bf16_f32 v13, v3, v5
	v_mul_f32_e32 v3, v46, v51
	v_mul_f32_e32 v5, v46, v50
	v_add_co_u32_e32 v16, vcc, 0x4000, v16
	v_cvt_pk_bf16_f32 v14, v3, v5
	v_mul_f32_e32 v3, v46, v49
	v_mul_f32_e32 v5, v46, v23
	v_cvt_pk_bf16_f32 v15, v3, v5
	v_addc_co_u32_e32 v17, vcc, 0, v17, vcc
	v_mov_b32_e32 v24, 0
	global_store_dwordx4 v[16:17], v[8:11], off offset:1024
	global_store_dwordx4 v[18:19], v[12:15], off offset:16
	v_mov_b32_e32 v25, 0
	v_mov_b64_e32 v[22:23], 0
	v_mov_b32_e32 v18, 0
	v_mov_b32_e32 v19, v24
	v_mov_b32_e32 v16, v24
	v_mov_b32_e32 v17, v24
	v_mov_b32_e32 v14, v24
	v_mov_b32_e32 v15, v24
	v_mov_b32_e32 v8, v24
	v_mov_b32_e32 v9, v24
	v_mov_b32_e32 v10, v24
	v_mov_b32_e32 v11, v24
	v_mov_b32_e32 v12, v24
	v_mov_b32_e32 v13, v24
	v_mov_b32_e32 v20, 0
	v_mov_b32_e32 v21, 0
	s_and_saveexec_b64 s[78:79], s[56:57]
	s_cbranch_execnz .LBB0_302
	s_or_b64 exec, exec, s[78:79]
	s_and_saveexec_b64 s[78:79], s[58:59]
	s_cbranch_execnz .LBB0_303

.LBB0_212:
	s_or_b64 exec, exec, s[78:79]
	v_ashrrev_i32_e32 v24, 6, v36
	v_xor_b32_e32 v24, v24, v27
	v_and_b32_e32 v25, 7, v29
	v_lshl_or_b32 v25, v24, 3, v25
	v_and_b32_e32 v3, 0x7ffffff0, v29
	v_and_b32_e32 v5, 3, v29
	v_lshlrev_b32_e32 v7, 1, v29
	v_and_b32_e32 v24, 8, v29
	v_lshlrev_b32_e32 v29, 1, v25
	v_mul_f32_e32 v25, 0xbfb8aa3b, v22
	v_exp_f32_e32 v25, v25
	v_and_or_b32 v3, v7, 8, v3
	v_lshlrev_b32_e32 v3, 1, v3
	v_xor_b32_e32 v3, v30, v3
	v_add_f32_e32 v25, 1.0, v25
	v_rcp_f32_e32 v25, v25
	v_lshlrev_b32_e32 v5, 1, v5
	v_add3_u32 v7, 0, v3, v5
	v_sub_f32_e32 v3, v37, v31
	v_mul_f32_e32 v25, v22, v25
	v_mul_f32_e32 v22, 0xbfb8aa3b, v23
	v_exp_f32_e32 v22, v22
	v_mul_f32_e32 v3, 0x3fb8aa3b, v3
	v_exp_f32_e32 v5, v3
	v_mul_f32_e32 v3, v26, v46
	v_add_f32_e32 v22, 1.0, v22
	v_rcp_f32_e32 v22, v22
	s_nop 0
	v_mul_f32_e32 v30, v23, v22
	v_mul_f32_e32 v22, 0xbfb8aa3b, v18
	v_exp_f32_e32 v22, v22
	v_mul_f32_e32 v50, v30, v30
	v_fmac_f32_e32 v50, v25, v25
	v_mul_f32_e32 v23, 0xbfb8aa3b, v21
	v_add_f32_e32 v22, 1.0, v22
	v_rcp_f32_e32 v22, v22
	v_exp_f32_e32 v23, v23
	v_mul_f32_e32 v31, v18, v22
	v_mul_f32_e32 v18, 0xbfb8aa3b, v19
	v_exp_f32_e32 v18, v18
	v_fmac_f32_e32 v50, v31, v31
	v_mul_f32_e32 v22, 0xbfb8aa3b, v20
	v_exp_f32_e32 v22, v22
	v_add_f32_e32 v18, 1.0, v18
	v_rcp_f32_e32 v18, v18
	v_add_f32_e32 v23, 1.0, v23
	v_add_f32_e32 v22, 1.0, v22
	v_rcp_f32_e32 v22, v22
	v_mul_f32_e32 v37, v19, v18
	v_mul_f32_e32 v18, 0xbfb8aa3b, v16
	v_exp_f32_e32 v18, v18
	v_mul_f32_e32 v19, 0xbfb8aa3b, v13
	v_exp_f32_e32 v19, v19
	v_fmac_f32_e32 v50, v37, v37
	v_add_f32_e32 v18, 1.0, v18
	v_rcp_f32_e32 v18, v18
	v_add_f32_e32 v19, 1.0, v19
	v_rcp_f32_e32 v19, v19
	v_rcp_f32_e32 v23, v23
	v_mul_f32_e32 v46, v16, v18
	v_mul_f32_e32 v16, 0xbfb8aa3b, v17
	v_exp_f32_e32 v16, v16
	v_mul_f32_e32 v18, 0xbfb8aa3b, v12
	v_exp_f32_e32 v18, v18
	v_fmac_f32_e32 v50, v46, v46
	v_add_f32_e32 v16, 1.0, v16
	v_rcp_f32_e32 v16, v16
	v_add_f32_e32 v18, 1.0, v18
	v_rcp_f32_e32 v18, v18
	v_mul_f32_e32 v47, v17, v16
	v_mul_f32_e32 v16, 0xbfb8aa3b, v14
	v_exp_f32_e32 v16, v16
	v_mul_f32_e32 v17, 0xbfb8aa3b, v11
	v_exp_f32_e32 v17, v17
	v_fmac_f32_e32 v50, v47, v47
	v_add_f32_e32 v16, 1.0, v16
	v_rcp_f32_e32 v16, v16
	v_add_f32_e32 v17, 1.0, v17
	v_rcp_f32_e32 v17, v17
	v_pk_mul_f32 v[12:13], v[12:13], v[18:19]
	v_mul_f32_e32 v48, v14, v16
	v_mul_f32_e32 v14, 0xbfb8aa3b, v15
	v_exp_f32_e32 v14, v14
	v_mul_f32_e32 v16, 0xbfb8aa3b, v10
	v_exp_f32_e32 v16, v16
	v_fmac_f32_e32 v50, v48, v48
	v_add_f32_e32 v14, 1.0, v14
	v_rcp_f32_e32 v14, v14
	v_add_f32_e32 v16, 1.0, v16
	v_rcp_f32_e32 v16, v16
	v_mul_f32_e32 v49, v15, v14
	v_mul_f32_e32 v14, 0xbfb8aa3b, v8
	v_mul_f32_e32 v15, 0xbfb8aa3b, v9
	v_exp_f32_e32 v14, v14
	v_exp_f32_e32 v15, v15
	v_fmac_f32_e32 v50, v49, v49
	v_pk_mul_f32 v[10:11], v[10:11], v[16:17]
	v_add_f32_e32 v14, 1.0, v14
	v_add_f32_e32 v15, 1.0, v15
	v_rcp_f32_e32 v14, v14
	v_rcp_f32_e32 v15, v15
	s_nop 0
	v_pk_mul_f32 v[8:9], v[8:9], v[14:15]
	s_nop 0
	v_pk_mul_f32 v[14:15], v[8:9], v[8:9]
	s_nop 0
	v_add_f32_e32 v14, v50, v14
	v_add_f32_e32 v50, v14, v15
	v_pk_mul_f32 v[14:15], v[10:11], v[10:11]
	s_nop 0
	v_add_f32_e32 v14, v50, v14
	v_add_f32_e32 v16, v14, v15
	v_pk_mul_f32 v[14:15], v[12:13], v[12:13]
	s_nop 0
	v_add_f32_e32 v14, v16, v14
	v_add_f32_e32 v18, v14, v15
	v_pk_mul_f32 v[14:15], v[20:21], v[22:23]
	s_nop 0
	v_pk_mul_f32 v[16:17], v[14:15], v[14:15]
	s_nop 0
	v_add_f32_e32 v16, v18, v16
	v_add_f32_e32 v16, v16, v17
	ds_bpermute_b32 v17, v45, v16
	s_waitcnt lgkmcnt(0)
	v_add_f32_e32 v16, v16, v17
	ds_bpermute_b32 v17, v44, v16
	s_waitcnt lgkmcnt(0)
	v_add_f32_e32 v16, v16, v17
	ds_bpermute_b32 v17, v43, v16
	s_waitcnt lgkmcnt(0)
	v_add_f32_e32 v16, v16, v17
	v_add_f32_e32 v16, 0x358637bd, v16
	v_cmp_gt_f32_e32 vcc, s85, v16
	v_mul_f32_e32 v17, 0x4b800000, v16
	s_nop 0
	v_cndmask_b32_e32 v16, v16, v17, vcc
	v_rsq_f32_e32 v16, v16
	s_nop 0
	v_mul_f32_e32 v17, 0x45800000, v16
	v_cndmask_b32_e32 v16, v16, v17, vcc
	v_mul_f32_e32 v17, v16, v15
	v_mul_f32_e32 v18, v16, v14
	v_mul_f32_e32 v19, v16, v13
	v_mul_f32_e32 v20, v16, v12
	v_mul_f32_e32 v21, v16, v11
	v_mul_f32_e32 v22, v16, v10
	v_mul_f32_e32 v23, v16, v9
	v_mul_f32_e32 v43, v16, v8
	v_mul_f32_e32 v44, v16, v49
	v_mul_f32_e32 v45, v16, v48
	v_mul_f32_e32 v47, v16, v47
	v_mul_f32_e32 v46, v16, v46
	v_mul_f32_e32 v37, v16, v37
	v_mul_f32_e32 v31, v16, v31
	v_mul_f32_e32 v30, v16, v30
	v_mul_f32_e32 v16, v16, v25
	v_cvt_pk_bf16_f32 v8, v16, v30
	v_cvt_pk_bf16_f32 v9, v31, v37
	v_cvt_pk_bf16_f32 v10, v46, v47
	v_cvt_pk_bf16_f32 v11, v45, v44
	v_cvt_pk_bf16_f32 v12, v43, v23
	v_cvt_pk_bf16_f32 v13, v22, v21
	v_cvt_pk_bf16_f32 v14, v20, v19
	v_cvt_pk_bf16_f32 v15, v18, v17
	ds_write_b128 v42, v[8:11]
	ds_write_b128 v42, v[12:15] offset:16
	v_mul_f32_e32 v8, v5, v16
	v_mul_u32_u24_e32 v9, 0x480, v27
	v_lshlrev_b32_e32 v9, 1, v9
	v_add3_u32 v7, v7, v24, v9
	v_mul_f32_e32 v10, v3, v16
	v_cvt_pk_bf16_f32 v8, v8, v10
	ds_write_b16 v7, v8 offset:34816
	v_add3_u32 v9, s88, v29, v9
	ds_write_b16_d16_hi v9, v8
	v_mul_f32_e32 v8, v5, v30
	v_mul_f32_e32 v10, v3, v30
	v_cvt_pk_bf16_f32 v8, v8, v10
	ds_write_b16 v7, v8 offset:34960
	ds_write_b16_d16_hi v9, v8 offset:144
	v_mul_f32_e32 v8, v5, v31
	v_mul_f32_e32 v10, v3, v31
	v_cvt_pk_bf16_f32 v8, v8, v10
	ds_write_b16 v7, v8 offset:35104
	ds_write_b16_d16_hi v9, v8 offset:288
	v_mul_f32_e32 v8, v5, v37
	v_mul_f32_e32 v10, v3, v37
	v_cvt_pk_bf16_f32 v8, v8, v10
	ds_write_b16 v7, v8 offset:35248
	ds_write_b16_d16_hi v9, v8 offset:432
	v_mul_f32_e32 v8, v5, v46
	v_mul_f32_e32 v10, v3, v46
	v_cvt_pk_bf16_f32 v8, v8, v10
	ds_write_b16 v7, v8 offset:35392
	ds_write_b16_d16_hi v9, v8 offset:576
	v_mul_f32_e32 v8, v5, v47
	v_mul_f32_e32 v10, v3, v47
	v_cvt_pk_bf16_f32 v8, v8, v10
	ds_write_b16 v7, v8 offset:35536
	ds_write_b16_d16_hi v9, v8 offset:720
	v_mul_f32_e32 v8, v5, v45
	v_mul_f32_e32 v10, v3, v45
	v_cvt_pk_bf16_f32 v8, v8, v10
	ds_write_b16 v7, v8 offset:35680
	ds_write_b16_d16_hi v9, v8 offset:864
	v_mul_f32_e32 v8, v5, v44
	v_mul_f32_e32 v10, v3, v44
	v_cvt_pk_bf16_f32 v8, v8, v10
	ds_write_b16 v7, v8 offset:35824
	ds_write_b16_d16_hi v9, v8 offset:1008
	v_mul_f32_e32 v8, v5, v43
	v_mul_f32_e32 v10, v3, v43
	v_cvt_pk_bf16_f32 v8, v8, v10
	ds_write_b16 v7, v8 offset:35968
	ds_write_b16_d16_hi v9, v8 offset:1152
	v_mul_f32_e32 v8, v5, v23
	v_mul_f32_e32 v10, v3, v23
	v_cvt_pk_bf16_f32 v8, v8, v10
	ds_write_b16 v7, v8 offset:36112
	ds_write_b16_d16_hi v9, v8 offset:1296
	v_mul_f32_e32 v8, v5, v22
	v_mul_f32_e32 v10, v3, v22
	v_cvt_pk_bf16_f32 v8, v8, v10
	ds_write_b16 v7, v8 offset:36256
	ds_write_b16_d16_hi v9, v8 offset:1440
	v_mul_f32_e32 v8, v5, v21
	v_mul_f32_e32 v10, v3, v21
	v_cvt_pk_bf16_f32 v8, v8, v10
	ds_write_b16 v7, v8 offset:36400
	ds_write_b16_d16_hi v9, v8 offset:1584
	v_mul_f32_e32 v8, v5, v20
	v_mul_f32_e32 v10, v3, v20
	v_cvt_pk_bf16_f32 v8, v8, v10
	ds_write_b16 v7, v8 offset:36544
	ds_write_b16_d16_hi v9, v8 offset:1728
	v_mul_f32_e32 v8, v5, v19
	v_mul_f32_e32 v10, v3, v19
	v_cvt_pk_bf16_f32 v8, v8, v10
	ds_write_b16 v7, v8 offset:36688
	ds_write_b16_d16_hi v9, v8 offset:1872
	v_mul_f32_e32 v8, v5, v18
	v_mul_f32_e32 v10, v3, v18
	v_cvt_pk_bf16_f32 v8, v8, v10
	ds_write_b16 v7, v8 offset:36832
	v_mul_f32_e32 v5, v5, v17
	ds_write_b16_d16_hi v9, v8 offset:2016
	v_bfe_u32 v8, v5, 16, 1
	v_add3_u32 v5, v5, v8, s83
	v_mul_f32_e32 v3, v3, v17
	ds_write_b16_d16_hi v7, v5 offset:36976
	v_bfe_u32 v5, v3, 16, 1
	v_add3_u32 v3, v3, v5, s83
	v_mov_b32_e32 v24, 0
	ds_write_b16_d16_hi v9, v3 offset:2160
	v_mov_b32_e32 v25, 0
	v_mov_b64_e32 v[20:21], 0
	v_mov_b32_e32 v18, 0
	v_mov_b32_e32 v19, v24
	v_mov_b32_e32 v16, v24
	v_mov_b32_e32 v17, v24
	v_mov_b32_e32 v14, v24
	v_mov_b32_e32 v15, v24
	v_mov_b32_e32 v12, v24
	v_mov_b32_e32 v13, v24
	v_mov_b32_e32 v10, v24
	v_mov_b32_e32 v11, v24
	v_mov_b32_e32 v8, v24
	v_mov_b32_e32 v9, v24
	v_mov_b32_e32 v22, 0
	v_mov_b32_e32 v23, 0
	s_and_saveexec_b64 s[78:79], s[56:57]
	s_cbranch_execnz .LBB0_305
	s_or_b64 exec, exec, s[78:79]
	s_and_saveexec_b64 s[56:57], s[58:59]
	s_cbranch_execnz .LBB0_306

.Lp3_pf_skip:
	s_waitcnt lgkmcnt(0)
	s_barrier
	v_bfe_u32 v37, v36, 5, 1
	v_or_b32_e32 v25, s36, v42
	v_lshlrev_b32_e32 v24, 3, v37
	v_mul_u32_u24_e32 v31, 0x110, v25
	v_mov_b32_e32 v0, 0
	s_andn2_b64 vcc, exec, s[64:65]
	v_mov_b32_e32 v1, 0
	v_mov_b64_e32 v[2:3], 0
	v_mov_b64_e32 v[4:5], 0
	v_mov_b64_e32 v[6:7], 0
	v_mov_b64_e32 v[8:9], 0
	v_mov_b64_e32 v[10:11], 0
	v_mov_b64_e32 v[12:13], 0
	v_mov_b64_e32 v[14:15], 0
	s_cbranch_vccnz .LBB0_219
	v_or_b32_e32 v0, s2, v42
	v_lshlrev_b32_e32 v4, 1, v24
	v_mul_u32_u24_e32 v0, 0x110, v0
	v_add3_u32 v26, s23, v0, v4
	ds_read_b128 v[0:3], v26
	v_add3_u32 v27, 0, v31, v4
	ds_read_b128 v[4:7], v27
	ds_read_b128 v[16:19], v26 offset:32
	ds_read_b128 v[20:23], v27 offset:32
	s_waitcnt lgkmcnt(2)
	v_mfma_f32_32x32x16_bf16 v[0:15], v[0:3], v[4:7], 0
	s_waitcnt lgkmcnt(0)
	v_mfma_f32_32x32x16_bf16 v[0:15], v[16:19], v[20:23], v[0:15]
	ds_read_b128 v[16:19], v26 offset:64
	ds_read_b128 v[20:23], v27 offset:64
	s_waitcnt lgkmcnt(0)
	v_mfma_f32_32x32x16_bf16 v[0:15], v[16:19], v[20:23], v[0:15]
	ds_read_b128 v[16:19], v26 offset:96
	ds_read_b128 v[20:23], v27 offset:96
	s_waitcnt lgkmcnt(0)
	v_mfma_f32_32x32x16_bf16 v[0:15], v[16:19], v[20:23], v[0:15]
	ds_read_b128 v[16:19], v26 offset:128
	ds_read_b128 v[20:23], v27 offset:128
	s_waitcnt lgkmcnt(0)
	v_mfma_f32_32x32x16_bf16 v[0:15], v[16:19], v[20:23], v[0:15]
	ds_read_b128 v[16:19], v26 offset:160
	ds_read_b128 v[20:23], v27 offset:160
	s_waitcnt lgkmcnt(0)
	v_mfma_f32_32x32x16_bf16 v[0:15], v[16:19], v[20:23], v[0:15]
	ds_read_b128 v[16:19], v26 offset:192
	ds_read_b128 v[20:23], v27 offset:192
	s_waitcnt lgkmcnt(0)
	v_mfma_f32_32x32x16_bf16 v[0:15], v[16:19], v[20:23], v[0:15]
	ds_read_b128 v[16:19], v26 offset:224
	ds_read_b128 v[20:23], v27 offset:224
	s_waitcnt lgkmcnt(0)
	v_mfma_f32_32x32x16_bf16 v[0:15], v[16:19], v[20:23], v[0:15]

.LBB0_290:
	v_and_b32_e32 v44, 63, v36
	v_mov_b32_e32 v0, 0
	s_andn2_b64 vcc, exec, s[54:55]
	v_lshlrev_b32_e32 v45, 1, v42
	v_mov_b32_e32 v1, 0
	v_mov_b64_e32 v[2:3], 0
	v_mov_b64_e32 v[4:5], 0
	v_mov_b64_e32 v[6:7], 0
	v_mov_b64_e32 v[8:9], 0
	v_mov_b64_e32 v[10:11], 0
	v_mov_b64_e32 v[12:13], 0
	v_mov_b64_e32 v[14:15], 0
	s_cbranch_vccnz .LBB0_293
	v_lshl_add_u32 v0, v42, 2, s20
	v_mov_b32_e32 v1, s21
	v_add_u32_e32 v2, 0x200, v0
	ds_read2_b32 v[22:23], v2 offset0:76 offset1:144
	v_add_u32_e32 v2, 0x400, v0
	ds_read2_b32 v[30:31], v2 offset0:84 offset1:152
	v_add_u32_e32 v2, 0x600, v0
	ds_read2_b32 v[90:91], v2 offset0:92 offset1:160
	v_add_u32_e32 v2, 0x800, v0
	ds_read2_b32 v[92:93], v2 offset0:100 offset1:168
	v_add_u32_e32 v2, 0xa00, v0
	ds_read2_b32 v[94:95], v2 offset0:108 offset1:176
	v_add_u32_e32 v2, 0xc00, v0
	ds_read2_b32 v[96:97], v2 offset0:116 offset1:184
	v_add_u32_e32 v2, 0xe00, v0
	ds_read2_b32 v[98:99], v2 offset0:124 offset1:192
	v_add_u32_e32 v2, 0x1000, v0
	ds_read2_b32 v[100:101], v2 offset0:132 offset1:200
	v_add_u32_e32 v2, 0x1400, v0
	ds_read2_b32 v[14:15], v0 offset0:68 offset1:136
	ds_read2_b32 v[102:103], v2 offset0:12 offset1:80
	ds_read2_b32 v[104:105], v2 offset0:148 offset1:216
	v_add_u32_e32 v2, 0x1800, v0
	ds_read2_b32 v[106:107], v2 offset0:28 offset1:96
	ds_read2_b32 v[108:109], v2 offset0:164 offset1:232
	v_add_u32_e32 v2, 0x1c00, v0
	ds_read2_b32 v[110:111], v2 offset0:44 offset1:112
	ds_read2_b32 v[112:113], v2 offset0:180 offset1:248
	ds_read_b32 v25, v0 offset:8432
	ds_read_b128 v[2:5], v1 offset:272
	ds_read_b128 v[6:9], v1 offset:288
	ds_read_b128 v[10:13], v1 offset:304
	ds_read_b128 v[18:21], v1 offset:320
	ds_read_b128 v[26:29], v1 offset:336
	ds_read_b128 v[46:49], v1 offset:352
	ds_read_b128 v[50:53], v1 offset:368
	ds_read_b128 v[54:57], v1 offset:384
	ds_read_b128 v[58:61], v1 offset:544
	ds_read_b128 v[62:65], v1 offset:560
	ds_read_b128 v[66:69], v1 offset:576
	ds_read_b128 v[70:73], v1 offset:592
	ds_read_b128 v[74:77], v1 offset:608
	ds_read_b128 v[78:81], v1 offset:624
	ds_read_b128 v[82:85], v1 offset:640
	ds_read_b128 v[86:89], v1 offset:656
	v_or_b32_e32 v0, s37, v42
	v_mul_lo_u32 v0, v0, s95
	v_add3_u32 v0, s22, v0, v45
	s_waitcnt lgkmcnt(14)
	v_xor_b32_e32 v17, 0x80000000, v14
	v_fma_f32 v16, v14, v4, -v15
	v_fma_f32 v15, v14, v5, -v22
	s_waitcnt lgkmcnt(7)
	v_fma_f32 v58, v14, v6, -v23
	v_fma_f32 v30, v14, v7, -v30
	v_fma_f32 v31, v14, v8, -v31
	v_fma_f32 v59, v14, v9, -v90
	v_fma_f32 v60, v14, v10, -v91
	v_fma_f32 v90, v14, v11, -v92
	v_fma_f32 v91, v14, v12, -v93
	v_fma_f32 v92, v14, v13, -v94
	v_fma_f32 v93, v14, v18, -v95
	v_fma_f32 v19, v14, v19, -v96
	v_fma_f32 v94, v14, v20, -v97
	v_fma_f32 v95, v14, v21, -v98
	v_fma_f32 v96, v14, v26, -v99
	v_fma_f32 v97, v14, v27, -v100
	v_fma_f32 v98, v14, v28, -v101
	v_fma_f32 v99, v14, v29, -v102
	v_fma_f32 v100, v14, v46, -v103
	v_fma_f32 v101, v14, v47, -v104
	v_fma_f32 v102, v14, v48, -v105
	v_fma_f32 v103, v14, v49, -v106
	v_fma_f32 v104, v14, v50, -v107
	v_fma_f32 v105, v14, v51, -v108
	v_fma_f32 v106, v14, v52, -v109
	v_fma_f32 v107, v14, v53, -v110
	v_fma_f32 v54, v14, v54, -v111
	v_fma_f32 v55, v14, v55, -v112
	v_fma_f32 v56, v14, v56, -v113
	v_fma_f32 v14, v14, v57, -v25
	ds_read_b128 v[2:5], v1 offset:832
	ds_read_b128 v[6:9], v1 offset:848
	ds_read_b128 v[10:13], v1 offset:864
	ds_read_b128 v[20:23], v1 offset:880
	ds_read_b128 v[26:29], v1 offset:896
	ds_read_b128 v[46:49], v1 offset:912
	ds_read_b128 v[50:53], v1 offset:928
	v_fma_f32 v18, -v16, v61, v15
	s_waitcnt lgkmcnt(13)
	v_fma_f32 v15, -v16, v62, v58
	v_fma_f32 v25, -v16, v63, v30
	v_fma_f32 v30, -v16, v64, v31
	v_fma_f32 v31, -v16, v65, v59
	s_waitcnt lgkmcnt(7)
	v_fma_f32 v14, -v16, v89, v14
	v_fma_f32 v108, -v16, v66, v60
	v_fma_f32 v90, -v16, v67, v90
	v_fma_f32 v91, -v16, v68, v91
	v_fma_f32 v92, -v16, v69, v92
	v_fma_f32 v93, -v16, v70, v93
	v_fma_f32 v109, -v16, v71, v19
	v_fma_f32 v94, -v16, v72, v94
	v_fma_f32 v95, -v16, v73, v95
	v_fma_f32 v96, -v16, v74, v96
	v_fma_f32 v97, -v16, v75, v97
	v_fma_f32 v98, -v16, v76, v98
	v_fma_f32 v99, -v16, v77, v99
	v_fma_f32 v100, -v16, v78, v100
	v_fma_f32 v101, -v16, v79, v101
	v_fma_f32 v102, -v16, v80, v102
	v_fma_f32 v103, -v16, v81, v103
	v_fma_f32 v82, -v16, v82, v104
	v_fma_f32 v83, -v16, v83, v105
	v_fma_f32 v84, -v16, v84, v106
	v_fma_f32 v85, -v16, v85, v107
	v_fma_f32 v86, -v16, v86, v54
	v_fma_f32 v87, -v16, v87, v55
	v_fma_f32 v88, -v16, v88, v56
	ds_read_b128 v[54:57], v1 offset:1104
	ds_read_b128 v[58:61], v1 offset:1120
	ds_read_b128 v[62:65], v1 offset:1136
	ds_read_b128 v[66:69], v1 offset:1152
	ds_read_b128 v[70:73], v1 offset:1168
	ds_read_b128 v[74:77], v1 offset:1184
	ds_read_b128 v[78:81], v1 offset:1200
	s_waitcnt lgkmcnt(13)
	v_fma_f32 v19, -v18, v2, v15
	v_fma_f32 v15, -v18, v3, v25
	v_fma_f32 v25, -v18, v4, v30
	v_fma_f32 v30, -v18, v5, v31
	s_waitcnt lgkmcnt(12)
	v_fma_f32 v31, -v18, v6, v108
	s_waitcnt lgkmcnt(6)
	v_fma_f32 v54, -v18, v7, v90
	v_fma_f32 v21, -v18, v21, v97
	v_fma_f32 v22, -v18, v22, v98
	v_fma_f32 v23, -v18, v23, v99
	v_fma_f32 v14, -v18, v53, v14
	v_fma_f32 v89, -v18, v8, v91
	v_fma_f32 v90, -v18, v9, v92
	v_fma_f32 v91, -v18, v10, v93
	v_fma_f32 v92, -v18, v11, v109
	v_fma_f32 v93, -v18, v12, v94
	v_fma_f32 v94, -v18, v13, v95
	v_fma_f32 v95, -v18, v20, v96
	v_fma_f32 v96, -v18, v26, v100
	v_fma_f32 v97, -v18, v27, v101
	v_fma_f32 v98, -v18, v28, v102
	v_fma_f32 v99, -v18, v29, v103
	v_fma_f32 v100, -v18, v46, v82
	v_fma_f32 v101, -v18, v47, v83
	v_fma_f32 v102, -v18, v48, v84
	v_fma_f32 v103, -v18, v49, v85
	v_fma_f32 v86, -v18, v50, v86
	v_fma_f32 v87, -v18, v51, v87
	v_fma_f32 v88, -v18, v52, v88
	ds_read_b128 v[2:5], v1 offset:1376
	ds_read_b128 v[6:9], v1 offset:1392
	ds_read_b128 v[10:13], v1 offset:1408
	ds_read_b128 v[26:29], v1 offset:1424
	ds_read_b128 v[46:49], v1 offset:1440
	ds_read_b128 v[50:53], v1 offset:1456
	ds_read_b128 v[82:85], v1 offset:1472
	v_fma_f32 v20, -v19, v55, v15
	s_waitcnt lgkmcnt(6)
	v_fma_f32 v2, -v19, v56, v25
	v_fma_f32 v3, -v19, v57, v30
	v_fma_f32 v15, -v19, v58, v31
	v_fma_f32 v25, -v19, v59, v54
	v_fma_f32 v30, -v19, v60, v89
	v_fma_f32 v31, -v19, v61, v90
	v_fma_f32 v22, -v19, v68, v22
	v_fma_f32 v23, -v19, v69, v23
	v_fma_f32 v14, -v19, v81, v14
	v_fma_f32 v89, -v19, v62, v91
	v_fma_f32 v90, -v19, v63, v92
	v_fma_f32 v91, -v19, v64, v93
	v_fma_f32 v92, -v19, v65, v94
	v_fma_f32 v93, -v19, v66, v95
	v_fma_f32 v94, -v19, v67, v21
	v_fma_f32 v95, -v19, v70, v96
	v_fma_f32 v96, -v19, v71, v97
	v_fma_f32 v97, -v19, v72, v98
	v_fma_f32 v98, -v19, v73, v99
	v_fma_f32 v99, -v19, v74, v100
	v_fma_f32 v100, -v19, v75, v101
	v_fma_f32 v101, -v19, v76, v102
	v_fma_f32 v102, -v19, v77, v103
	v_fma_f32 v86, -v19, v78, v86
	v_fma_f32 v87, -v19, v79, v87
	v_fma_f32 v88, -v19, v80, v88
	ds_read_b128 v[54:57], v1 offset:1648
	ds_read_b128 v[58:61], v1 offset:1664
	ds_read_b128 v[62:65], v1 offset:1680
	ds_read_b128 v[66:69], v1 offset:1696
	ds_read_b128 v[70:73], v1 offset:1712
	ds_read_b128 v[74:77], v1 offset:1728
	ds_read_b128 v[78:81], v1 offset:1744
	v_fma_f32 v21, -v20, v4, v2
	s_waitcnt lgkmcnt(6)
	v_fma_f32 v54, -v20, v5, v3
	v_fma_f32 v15, -v20, v6, v15
	v_fma_f32 v25, -v20, v7, v25
	v_fma_f32 v30, -v20, v8, v30
	v_fma_f32 v31, -v20, v9, v31
	v_fma_f32 v55, -v20, v10, v89
	v_fma_f32 v56, -v20, v11, v90
	v_fma_f32 v23, -v20, v29, v23
	v_fma_f32 v14, -v20, v85, v14
	v_fma_f32 v89, -v20, v12, v91
	v_fma_f32 v90, -v20, v13, v92
	v_fma_f32 v91, -v20, v26, v93
	v_fma_f32 v92, -v20, v27, v94
	v_fma_f32 v93, -v20, v28, v22
	v_fma_f32 v94, -v20, v46, v95
	v_fma_f32 v95, -v20, v47, v96
	v_fma_f32 v96, -v20, v48, v97
	v_fma_f32 v97, -v20, v49, v98
	v_fma_f32 v98, -v20, v50, v99
	v_fma_f32 v99, -v20, v51, v100
	v_fma_f32 v100, -v20, v52, v101
	v_fma_f32 v101, -v20, v53, v102
	v_fma_f32 v82, -v20, v82, v86
	v_fma_f32 v83, -v20, v83, v87
	v_fma_f32 v84, -v20, v84, v88
	ds_read_b128 v[2:5], v1 offset:1936
	ds_read_b128 v[6:9], v1 offset:1952
	ds_read_b128 v[10:13], v1 offset:1968
	ds_read_b128 v[26:29], v1 offset:1984
	ds_read_b128 v[46:49], v1 offset:2000
	ds_read_b128 v[50:53], v1 offset:2016
	v_fma_f32 v22, -v21, v57, v54
	s_waitcnt lgkmcnt(11)
	v_fma_f32 v15, -v21, v58, v15
	v_fma_f32 v25, -v21, v59, v25
	v_fma_f32 v30, -v21, v60, v30
	v_fma_f32 v31, -v21, v61, v31
	s_waitcnt lgkmcnt(6)
	v_fma_f32 v14, -v21, v81, v14
	v_fma_f32 v85, -v21, v62, v55
	v_fma_f32 v86, -v21, v63, v56
	v_fma_f32 v87, -v21, v64, v89
	v_fma_f32 v88, -v21, v65, v90
	v_fma_f32 v89, -v21, v66, v91
	v_fma_f32 v90, -v21, v67, v92
	v_fma_f32 v91, -v21, v68, v93
	v_fma_f32 v92, -v21, v69, v23
	v_fma_f32 v93, -v21, v70, v94
	v_fma_f32 v94, -v21, v71, v95
	v_fma_f32 v95, -v21, v72, v96
	v_fma_f32 v96, -v21, v73, v97
	v_fma_f32 v97, -v21, v74, v98
	v_fma_f32 v98, -v21, v75, v99
	v_fma_f32 v99, -v21, v76, v100
	v_fma_f32 v100, -v21, v77, v101
	v_fma_f32 v78, -v21, v78, v82
	v_fma_f32 v79, -v21, v79, v83
	v_fma_f32 v80, -v21, v80, v84
	ds_read_b128 v[54:57], v1 offset:2208
	ds_read_b128 v[58:61], v1 offset:2224
	ds_read_b128 v[62:65], v1 offset:2240
	ds_read_b128 v[66:69], v1 offset:2256
	ds_read_b128 v[70:73], v1 offset:2272
	ds_read_b128 v[74:77], v1 offset:2288
	s_waitcnt lgkmcnt(11)
	v_fma_f32 v23, -v22, v2, v15
	v_fma_f32 v15, -v22, v3, v25
	s_waitcnt lgkmcnt(5)
	v_fma_f32 v54, -v22, v4, v30
	v_fma_f32 v26, -v22, v26, v93
	v_fma_f32 v27, -v22, v27, v94
	v_fma_f32 v14, -v22, v53, v14
	v_fma_f32 v81, -v22, v5, v31
	v_fma_f32 v82, -v22, v6, v85
	v_fma_f32 v83, -v22, v7, v86
	v_fma_f32 v84, -v22, v8, v87
	v_fma_f32 v85, -v22, v9, v88
	v_fma_f32 v86, -v22, v10, v89
	v_fma_f32 v87, -v22, v11, v90
	v_fma_f32 v88, -v22, v12, v91
	v_fma_f32 v89, -v22, v13, v92
	v_fma_f32 v90, -v22, v28, v95
	v_fma_f32 v91, -v22, v29, v96
	v_fma_f32 v92, -v22, v46, v97
	v_fma_f32 v93, -v22, v47, v98
	v_fma_f32 v94, -v22, v48, v99
	v_fma_f32 v95, -v22, v49, v100
	v_fma_f32 v78, -v22, v50, v78
	v_fma_f32 v79, -v22, v51, v79
	v_fma_f32 v80, -v22, v52, v80
	ds_read_b128 v[2:5], v1 offset:2480
	ds_read_b128 v[6:9], v1 offset:2496
	ds_read_b128 v[10:13], v1 offset:2512
	ds_read_b128 v[28:31], v1 offset:2528
	ds_read_b128 v[46:49], v1 offset:2544
	ds_read_b128 v[50:53], v1 offset:2560
	v_fma_f32 v25, -v23, v55, v15
	s_waitcnt lgkmcnt(5)
	v_fma_f32 v2, -v23, v56, v54
	v_fma_f32 v3, -v23, v57, v81
	v_fma_f32 v15, -v23, v58, v82
	v_fma_f32 v27, -v23, v67, v27
	v_fma_f32 v14, -v23, v77, v14
	v_fma_f32 v81, -v23, v59, v83
	v_fma_f32 v82, -v23, v60, v84
	v_fma_f32 v83, -v23, v61, v85
	v_fma_f32 v84, -v23, v62, v86
	v_fma_f32 v85, -v23, v63, v87
	v_fma_f32 v86, -v23, v64, v88
	v_fma_f32 v87, -v23, v65, v89
	v_fma_f32 v88, -v23, v66, v26
	v_fma_f32 v89, -v23, v68, v90
	v_fma_f32 v90, -v23, v69, v91
	v_fma_f32 v91, -v23, v70, v92
	v_fma_f32 v92, -v23, v71, v93
	v_fma_f32 v93, -v23, v72, v94
	v_fma_f32 v94, -v23, v73, v95
	v_fma_f32 v78, -v23, v74, v78
	v_fma_f32 v79, -v23, v75, v79
	v_fma_f32 v80, -v23, v76, v80
	ds_read_b128 v[54:57], v1 offset:2752
	ds_read_b128 v[58:61], v1 offset:2768
	ds_read_b128 v[62:65], v1 offset:2784
	ds_read_b128 v[66:69], v1 offset:2800
	ds_read_b128 v[70:73], v1 offset:2816
	ds_read_b128 v[74:77], v1 offset:2832
	v_fma_f32 v26, -v25, v4, v2
	s_waitcnt lgkmcnt(5)
	v_fma_f32 v54, -v25, v5, v3
	v_fma_f32 v15, -v25, v6, v15
	v_fma_f32 v55, -v25, v7, v81
	v_fma_f32 v56, -v25, v8, v82
	v_fma_f32 v28, -v25, v28, v88
	v_fma_f32 v29, -v25, v29, v27
	v_fma_f32 v30, -v25, v30, v89
	v_fma_f32 v31, -v25, v31, v90
	v_fma_f32 v14, -v25, v53, v14
	v_fma_f32 v81, -v25, v9, v83
	v_fma_f32 v82, -v25, v10, v84
	v_fma_f32 v83, -v25, v11, v85
	v_fma_f32 v84, -v25, v12, v86
	v_fma_f32 v85, -v25, v13, v87
	v_fma_f32 v86, -v25, v46, v91
	v_fma_f32 v87, -v25, v47, v92
	v_fma_f32 v88, -v25, v48, v93
	v_fma_f32 v89, -v25, v49, v94
	v_fma_f32 v78, -v25, v50, v78
	v_fma_f32 v79, -v25, v51, v79
	v_fma_f32 v80, -v25, v52, v80
	ds_read_b128 v[2:5], v1 offset:3040
	ds_read_b128 v[6:9], v1 offset:3056
	ds_read_b128 v[10:13], v1 offset:3072
	ds_read_b128 v[46:49], v1 offset:3088
	ds_read_b128 v[50:53], v1 offset:3104
	v_fma_f32 v27, -v26, v57, v54
	s_waitcnt lgkmcnt(9)
	v_fma_f32 v15, -v26, v58, v15
	s_waitcnt lgkmcnt(5)
	v_fma_f32 v14, -v26, v77, v14
	v_fma_f32 v90, -v26, v59, v55
	v_fma_f32 v91, -v26, v60, v56
	v_fma_f32 v81, -v26, v61, v81
	v_fma_f32 v82, -v26, v62, v82
	v_fma_f32 v83, -v26, v63, v83
	v_fma_f32 v84, -v26, v64, v84
	v_fma_f32 v85, -v26, v65, v85
	v_fma_f32 v92, -v26, v66, v28
	v_fma_f32 v93, -v26, v67, v29
	v_fma_f32 v94, -v26, v68, v30
	v_fma_f32 v95, -v26, v69, v31
	v_fma_f32 v70, -v26, v70, v86
	v_fma_f32 v71, -v26, v71, v87
	v_fma_f32 v72, -v26, v72, v88
	v_fma_f32 v73, -v26, v73, v89
	v_fma_f32 v74, -v26, v74, v78
	v_fma_f32 v75, -v26, v75, v79
	v_fma_f32 v76, -v26, v76, v80
	ds_read_b128 v[28:31], v1 offset:3312
	ds_read_b128 v[54:57], v1 offset:3328
	ds_read_b128 v[58:61], v1 offset:3344
	ds_read_b128 v[62:65], v1 offset:3360
	ds_read_b128 v[66:69], v1 offset:3376
	s_waitcnt lgkmcnt(4)
	v_fma_f32 v28, -v27, v2, v15
	v_fma_f32 v15, -v27, v3, v90
	v_fma_f32 v14, -v27, v53, v14
	v_fma_f32 v77, -v27, v4, v91
	v_fma_f32 v78, -v27, v5, v81
	v_fma_f32 v79, -v27, v6, v82
	v_fma_f32 v80, -v27, v7, v83
	v_fma_f32 v81, -v27, v8, v84
	v_fma_f32 v82, -v27, v9, v85
	v_fma_f32 v83, -v27, v10, v92
	v_fma_f32 v84, -v27, v11, v93
	v_fma_f32 v85, -v27, v12, v94
	v_fma_f32 v86, -v27, v13, v95
	v_fma_f32 v70, -v27, v46, v70
	v_fma_f32 v71, -v27, v47, v71
	v_fma_f32 v72, -v27, v48, v72
	v_fma_f32 v73, -v27, v49, v73
	v_fma_f32 v74, -v27, v50, v74
	v_fma_f32 v75, -v27, v51, v75
	v_fma_f32 v76, -v27, v52, v76
	ds_read_b128 v[2:5], v1 offset:3584
	ds_read_b128 v[6:9], v1 offset:3600
	ds_read_b128 v[10:13], v1 offset:3616
	ds_read_b128 v[46:49], v1 offset:3632
	ds_read_b128 v[50:53], v1 offset:3648
	v_fma_f32 v29, -v28, v29, v15
	s_waitcnt lgkmcnt(4)
	v_fma_f32 v2, -v28, v30, v77
	v_fma_f32 v3, -v28, v31, v78
	v_fma_f32 v15, -v28, v54, v79
	v_fma_f32 v30, -v28, v55, v80
	v_fma_f32 v14, -v28, v69, v14
	v_fma_f32 v77, -v28, v56, v81
	v_fma_f32 v78, -v28, v57, v82
	v_fma_f32 v79, -v28, v58, v83
	v_fma_f32 v80, -v28, v59, v84
	v_fma_f32 v81, -v28, v60, v85
	v_fma_f32 v82, -v28, v61, v86
	v_fma_f32 v83, -v28, v62, v70
	v_fma_f32 v84, -v28, v63, v71
	v_fma_f32 v85, -v28, v64, v72
	v_fma_f32 v86, -v28, v65, v73
	v_fma_f32 v74, -v28, v66, v74
	v_fma_f32 v75, -v28, v67, v75
	v_fma_f32 v76, -v28, v68, v76
	ds_read_b128 v[54:57], v1 offset:3856
	ds_read_b128 v[58:61], v1 offset:3872
	ds_read_b128 v[62:65], v1 offset:3888
	ds_read_b128 v[66:69], v1 offset:3904
	ds_read_b128 v[70:73], v1 offset:3920
	v_fma_f32 v31, -v29, v4, v2
	s_waitcnt lgkmcnt(4)
	v_fma_f32 v54, -v29, v5, v3
	v_fma_f32 v15, -v29, v6, v15
	v_fma_f32 v30, -v29, v7, v30
	v_fma_f32 v55, -v29, v8, v77
	v_fma_f32 v56, -v29, v9, v78
	v_fma_f32 v46, -v29, v46, v83
	v_fma_f32 v52, -v29, v52, v76
	v_fma_f32 v14, -v29, v53, v14
	v_fma_f32 v77, -v29, v10, v79
	v_fma_f32 v78, -v29, v11, v80
	v_fma_f32 v79, -v29, v12, v81
	v_fma_f32 v80, -v29, v13, v82
	v_fma_f32 v81, -v29, v47, v84
	v_fma_f32 v82, -v29, v48, v85
	v_fma_f32 v83, -v29, v49, v86
	v_fma_f32 v74, -v29, v50, v74
	v_fma_f32 v75, -v29, v51, v75
	ds_read_b128 v[2:5], v1 offset:4144
	ds_read_b128 v[6:9], v1 offset:4160
	ds_read_b128 v[10:13], v1 offset:4176
	ds_read_b128 v[48:51], v1 offset:4192
	v_fma_f32 v47, -v31, v57, v54
	s_waitcnt lgkmcnt(7)
	v_fma_f32 v15, -v31, v58, v15
	s_waitcnt lgkmcnt(5)
	v_fma_f32 v46, -v31, v66, v46
	s_waitcnt lgkmcnt(4)
	v_fma_f32 v14, -v31, v73, v14
	v_fma_f32 v76, -v31, v59, v30
	v_fma_f32 v84, -v31, v60, v55
	v_fma_f32 v85, -v31, v61, v56
	v_fma_f32 v77, -v31, v62, v77
	v_fma_f32 v78, -v31, v63, v78
	v_fma_f32 v79, -v31, v64, v79
	v_fma_f32 v80, -v31, v65, v80
	v_fma_f32 v81, -v31, v67, v81
	v_fma_f32 v68, -v31, v68, v82
	v_fma_f32 v69, -v31, v69, v83
	v_fma_f32 v70, -v31, v70, v74
	v_fma_f32 v71, -v31, v71, v75
	v_fma_f32 v72, -v31, v72, v52
	ds_read_b128 v[52:55], v1 offset:4416
	ds_read_b128 v[56:59], v1 offset:4432
	ds_read_b128 v[60:63], v1 offset:4448
	ds_read_b128 v[64:67], v1 offset:4464
	s_waitcnt lgkmcnt(7)
	v_fma_f32 v30, -v47, v2, v15
	v_fma_f32 v15, -v47, v3, v76
	s_waitcnt lgkmcnt(3)
	v_fma_f32 v52, -v47, v4, v84
	v_fma_f32 v48, -v47, v48, v70
	v_fma_f32 v49, -v47, v49, v71
	v_fma_f32 v50, -v47, v50, v72
	v_fma_f32 v14, -v47, v51, v14
	v_fma_f32 v73, -v47, v5, v85
	v_fma_f32 v74, -v47, v6, v77
	v_fma_f32 v75, -v47, v7, v78
	v_fma_f32 v76, -v47, v8, v79
	v_fma_f32 v77, -v47, v9, v80
	v_fma_f32 v78, -v47, v10, v46
	v_fma_f32 v79, -v47, v11, v81
	v_fma_f32 v80, -v47, v12, v68
	v_fma_f32 v81, -v47, v13, v69
	ds_read_b128 v[2:5], v1 offset:4688
	ds_read_b128 v[6:9], v1 offset:4704
	ds_read_b128 v[10:13], v1 offset:4720
	ds_read_b128 v[68:71], v1 offset:4736
	v_fma_f32 v46, -v30, v53, v15
	s_waitcnt lgkmcnt(3)
	v_fma_f32 v2, -v30, v54, v52
	v_fma_f32 v3, -v30, v55, v73
	v_fma_f32 v15, -v30, v56, v74
	v_fma_f32 v14, -v30, v67, v14
	v_fma_f32 v72, -v30, v57, v75
	v_fma_f32 v73, -v30, v58, v76
	v_fma_f32 v74, -v30, v59, v77
	v_fma_f32 v75, -v30, v60, v78
	v_fma_f32 v76, -v30, v61, v79
	v_fma_f32 v77, -v30, v62, v80
	v_fma_f32 v78, -v30, v63, v81
	v_fma_f32 v64, -v30, v64, v48
	v_fma_f32 v65, -v30, v65, v49
	v_fma_f32 v66, -v30, v66, v50
	ds_read_b128 v[48:51], v1 offset:4960
	ds_read_b128 v[52:55], v1 offset:4976
	ds_read_b128 v[56:59], v1 offset:4992
	ds_read_b128 v[60:63], v1 offset:5008
	s_waitcnt lgkmcnt(3)
	v_fma_f32 v48, -v46, v4, v2
	v_fma_f32 v49, -v46, v5, v3
	v_fma_f32 v15, -v46, v6, v15
	v_fma_f32 v50, -v46, v7, v72
	v_fma_f32 v14, -v46, v71, v14
	v_fma_f32 v67, -v46, v8, v73
	v_fma_f32 v72, -v46, v9, v74
	v_fma_f32 v73, -v46, v10, v75
	v_fma_f32 v74, -v46, v11, v76
	v_fma_f32 v75, -v46, v12, v77
	v_fma_f32 v76, -v46, v13, v78
	v_fma_f32 v64, -v46, v68, v64
	v_fma_f32 v65, -v46, v69, v65
	v_fma_f32 v66, -v46, v70, v66
	ds_read_b128 v[2:5], v1 offset:5248
	ds_read_b128 v[6:9], v1 offset:5264
	ds_read_b128 v[10:13], v1 offset:5280
	v_fma_f32 v49, -v48, v51, v49
	s_waitcnt lgkmcnt(5)
	v_fma_f32 v15, -v48, v52, v15
	s_waitcnt lgkmcnt(3)
	v_fma_f32 v14, -v48, v63, v14
	v_fma_f32 v68, -v48, v53, v50
	v_fma_f32 v67, -v48, v54, v67
	v_fma_f32 v69, -v48, v55, v72
	v_fma_f32 v70, -v48, v56, v73
	v_fma_f32 v71, -v48, v57, v74
	v_fma_f32 v72, -v48, v58, v75
	v_fma_f32 v73, -v48, v59, v76
	v_fma_f32 v64, -v48, v60, v64
	v_fma_f32 v65, -v48, v61, v65
	v_fma_f32 v62, -v48, v62, v66
	ds_read_b128 v[50:53], v1 offset:5520
	ds_read_b128 v[54:57], v1 offset:5536
	ds_read_b128 v[58:61], v1 offset:5552
	s_waitcnt lgkmcnt(2)
	v_fma_f32 v50, -v49, v2, v15
	v_fma_f32 v15, -v49, v3, v68
	v_fma_f32 v14, -v49, v13, v14
	v_fma_f32 v63, -v49, v4, v67
	v_fma_f32 v66, -v49, v5, v69
	v_fma_f32 v67, -v49, v6, v70
	v_fma_f32 v68, -v49, v7, v71
	v_fma_f32 v69, -v49, v8, v72
	v_fma_f32 v70, -v49, v9, v73
	v_fma_f32 v64, -v49, v10, v64
	v_fma_f32 v65, -v49, v11, v65
	v_fma_f32 v62, -v49, v12, v62
	ds_read_b128 v[2:5], v1 offset:5792
	ds_read_b128 v[6:9], v1 offset:5808
	ds_read_b128 v[10:13], v1 offset:5824
	v_fma_f32 v51, -v50, v51, v15
	s_waitcnt lgkmcnt(2)
	v_fma_f32 v2, -v50, v52, v63
	v_fma_f32 v3, -v50, v53, v66
	v_fma_f32 v15, -v50, v54, v67
	v_fma_f32 v14, -v50, v61, v14
	v_fma_f32 v66, -v50, v55, v68
	v_fma_f32 v67, -v50, v56, v69
	v_fma_f32 v68, -v50, v57, v70
	v_fma_f32 v64, -v50, v58, v64
	v_fma_f32 v65, -v50, v59, v65
	v_fma_f32 v69, -v50, v60, v62
	ds_read_b128 v[52:55], v1 offset:6064
	ds_read_b128 v[56:59], v1 offset:6080
	ds_read_b128 v[60:63], v1 offset:6096
	s_waitcnt lgkmcnt(2)
	v_fma_f32 v52, -v51, v4, v2
	v_fma_f32 v53, -v51, v5, v3
	v_fma_f32 v15, -v51, v6, v15
	v_fma_f32 v54, -v51, v7, v66
	v_fma_f32 v10, -v51, v10, v64
	v_fma_f32 v11, -v51, v11, v65
	v_fma_f32 v12, -v51, v12, v69
	v_fma_f32 v13, -v51, v13, v14
	v_fma_f32 v66, -v51, v8, v67
	v_fma_f32 v67, -v51, v9, v68
	ds_read_b128 v[2:5], v1 offset:6352
	ds_read_b128 v[6:9], v1 offset:6368
	v_fma_f32 v53, -v52, v55, v53
	s_waitcnt lgkmcnt(3)
	v_fma_f32 v14, -v52, v56, v15
	v_fma_f32 v15, -v52, v57, v54
	v_fma_f32 v54, -v52, v58, v66
	v_fma_f32 v55, -v52, v59, v67
	s_waitcnt lgkmcnt(2)
	v_fma_f32 v56, -v52, v60, v10
	v_fma_f32 v58, -v52, v61, v11
	v_fma_f32 v59, -v52, v62, v12
	v_fma_f32 v64, -v52, v63, v13
	ds_read_b128 v[10:13], v1 offset:6624
	ds_read_b128 v[60:63], v1 offset:6640
	s_waitcnt lgkmcnt(3)
	v_fma_f32 v57, -v53, v2, v14
	s_waitcnt lgkmcnt(1)
	v_fma_f32 v10, -v53, v3, v15
	v_fma_f32 v14, -v53, v4, v54
	v_fma_f32 v15, -v53, v5, v55
	v_fma_f32 v54, -v53, v6, v56
	v_fma_f32 v55, -v53, v7, v58
	v_fma_f32 v56, -v53, v8, v59
	v_fma_f32 v58, -v53, v9, v64
	ds_read_b128 v[2:5], v1 offset:6896
	ds_read_b128 v[6:9], v1 offset:6912
	v_fma_f32 v59, -v57, v11, v10
	s_waitcnt lgkmcnt(1)
	v_fma_f32 v2, -v57, v12, v14
	v_fma_f32 v3, -v57, v13, v15
	v_fma_f32 v14, -v57, v60, v54
	v_fma_f32 v15, -v57, v61, v55
	v_fma_f32 v54, -v57, v62, v56
	v_fma_f32 v55, -v57, v63, v58
	ds_read_b128 v[10:13], v1 offset:7168
	ds_read_b128 v[62:65], v1 offset:7184
	v_fma_f32 v61, -v59, v4, v2
	s_waitcnt lgkmcnt(1)
	v_fma_f32 v10, -v59, v5, v3
	v_fma_f32 v6, -v59, v6, v14
	v_fma_f32 v7, -v59, v7, v15
	v_fma_f32 v8, -v59, v8, v54
	v_fma_f32 v9, -v59, v9, v55
	ds_read_b128 v[2:5], v1 offset:7456
	v_fma_f32 v60, -v61, v13, v10
	s_waitcnt lgkmcnt(1)
	v_fma_f32 v10, -v61, v62, v6
	v_fma_f32 v11, -v61, v63, v7
	v_fma_f32 v12, -v61, v64, v8
	v_fma_f32 v13, -v61, v65, v9
	ds_read_b128 v[6:9], v1 offset:7728
	s_waitcnt lgkmcnt(1)
	v_fma_f32 v58, -v60, v2, v10
	s_waitcnt lgkmcnt(0)
	v_fma_f32 v6, -v60, v3, v11
	v_fma_f32 v10, -v60, v4, v12
	v_fma_f32 v11, -v60, v5, v13
	ds_read_b128 v[2:5], v1 offset:8000
	v_fma_f32 v56, -v58, v7, v6
	s_waitcnt lgkmcnt(0)
	v_fma_f32 v2, -v58, v8, v10
	v_fma_f32 v3, -v58, v9, v11
	ds_read_b128 v[6:9], v1 offset:8272
	v_fma_f32 v55, -v56, v4, v2
	v_fma_f32 v1, -v56, v5, v3
	s_waitcnt lgkmcnt(0)
	v_fma_f32 v54, -v55, v9, v1
	v_add_u32_e32 v1, s1, v45
	v_cvt_pk_bf16_f32 v2, v17, v16
	ds_write_b16 v1, v2 offset:144
	ds_write_b16_d16_hi v1, v2 offset:288
	v_cvt_pk_bf16_f32 v2, v18, v19
	ds_write_b16 v1, v2 offset:432
	ds_write_b16_d16_hi v1, v2 offset:576
	v_cvt_pk_bf16_f32 v2, v20, v21
	ds_write_b16 v1, v2 offset:720
	ds_write_b16_d16_hi v1, v2 offset:864
	v_cvt_pk_bf16_f32 v2, v22, v23
	ds_write_b16 v1, v2 offset:1008
	ds_write_b16_d16_hi v1, v2 offset:1152
	v_cvt_pk_bf16_f32 v2, v25, v26
	ds_write_b16 v1, v2 offset:1296
	ds_write_b16_d16_hi v1, v2 offset:1440
	v_cvt_pk_bf16_f32 v2, v27, v28
	ds_write_b16 v1, v2 offset:1584
	ds_write_b16_d16_hi v1, v2 offset:1728
	v_cvt_pk_bf16_f32 v2, v29, v31
	ds_write_b16 v1, v2 offset:1872
	ds_write_b16_d16_hi v1, v2 offset:2016
	v_cvt_pk_bf16_f32 v2, v47, v30
	ds_write_b16 v1, v2 offset:2160
	ds_write_b16_d16_hi v1, v2 offset:2304
	v_cvt_pk_bf16_f32 v2, v46, v48
	ds_write_b16 v1, v2 offset:2448
	ds_write_b16_d16_hi v1, v2 offset:2592
	v_cvt_pk_bf16_f32 v2, v49, v50
	ds_write_b16 v1, v2 offset:2736
	ds_write_b16_d16_hi v1, v2 offset:2880
	v_cvt_pk_bf16_f32 v2, v51, v52
	ds_write_b16 v1, v2 offset:3024
	ds_write_b16_d16_hi v1, v2 offset:3168
	v_cvt_pk_bf16_f32 v2, v53, v57
	ds_write_b16 v1, v2 offset:3312
	ds_write_b16_d16_hi v1, v2 offset:3456
	v_cvt_pk_bf16_f32 v2, v59, v61
	ds_write_b16 v1, v2 offset:3600
	ds_write_b16_d16_hi v1, v2 offset:3744
	v_cvt_pk_bf16_f32 v2, v60, v58
	ds_write_b16 v1, v2 offset:3888
	ds_write_b16_d16_hi v1, v2 offset:4032
	v_cvt_pk_bf16_f32 v2, v56, v55
	ds_write_b16 v1, v2 offset:4176
	ds_write_b16_d16_hi v1, v2 offset:4320
	v_bfe_u32 v2, v54, 16, 1
	v_add3_u32 v2, v54, v2, s83
	ds_write_b16 v1, v197
	ds_write_b16_d16_hi v1, v2 offset:4464
	s_waitcnt lgkmcnt(0)
	v_mov_b32_e32 v1, 0x3f80
	ds_write_b16 v0, v1
	v_mov_b32_e32 v15, 0
	s_andn2_b64 vcc, exec, s[70:71]
	v_mov_b32_e32 v14, 0
	v_mov_b64_e32 v[12:13], 0
	v_mov_b64_e32 v[10:11], 0
	v_mov_b64_e32 v[8:9], 0
	v_mov_b64_e32 v[6:7], 0
	v_mov_b64_e32 v[4:5], 0
	v_mov_b64_e32 v[2:3], 0
	v_mov_b64_e32 v[0:1], 0
	s_cbranch_vccnz .LBB0_293
	v_mul_u32_u24_e32 v0, 0x110, v42
	v_lshlrev_b32_e32 v1, 2, v24
	v_add3_u32 v62, s9, v0, v1
	ds_read_b128 v[0:3], v62 offset:8704
	ds_read_b128 v[4:7], v62 offset:8720
	v_cmp_gt_u32_e32 vcc, 32, v44
	v_cmp_eq_u32_e64 s[54:55], v24, v42
	s_waitcnt lgkmcnt(1)
	v_cvt_pk_bf16_f32 v0, v0, v1
	v_cvt_pk_bf16_f32 v1, v2, v3
	s_waitcnt lgkmcnt(0)
	v_cvt_pk_bf16_f32 v2, v4, v5
	v_mov_b32_e32 v4, v197
	v_cvt_pk_bf16_f32 v3, v6, v7
	v_cndmask_b32_e64 v5, 0, 1.0, s[54:55]
	v_cndmask_b32_e32 v4, v23, v4, vcc
	v_add_f32_e32 v4, v5, v4
	v_or_b32_e32 v5, 1, v24
	v_cmp_eq_u32_e64 s[54:55], v5, v42
	s_nop 1
	v_cndmask_b32_e64 v5, 0, 1.0, s[54:55]
	v_cndmask_b32_e32 v6, v25, v17, vcc
	v_add_f32_e32 v5, v5, v6
	v_or_b32_e32 v6, 2, v24
	v_cmp_eq_u32_e64 s[54:55], v6, v42
	v_cndmask_b32_e32 v7, v26, v16, vcc
	v_cndmask_b32_e32 v8, v27, v18, vcc
	v_cndmask_b32_e64 v6, 0, 1.0, s[54:55]
	v_add_f32_e32 v6, v6, v7
	v_or_b32_e32 v7, 3, v24
	v_cmp_eq_u32_e64 s[54:55], v7, v42
	v_cndmask_b32_e32 v9, v28, v19, vcc
	v_cndmask_b32_e32 v10, v29, v20, vcc
	v_cndmask_b32_e64 v7, 0, 1.0, s[54:55]
	v_add_f32_e32 v7, v7, v8
	v_or_b32_e32 v8, 4, v24
	v_cmp_eq_u32_e64 s[54:55], v8, v42
	v_cvt_pk_bf16_f32 v4, v4, v5
	v_cvt_pk_bf16_f32 v5, v6, v7
	s_nop 0
	v_cndmask_b32_e32 v11, v31, v21, vcc
	v_cndmask_b32_e64 v8, 0, 1.0, s[54:55]
	v_add_f32_e32 v8, v8, v9
	v_or_b32_e32 v9, 5, v24
	v_cmp_eq_u32_e64 s[54:55], v9, v42
	v_cndmask_b32_e32 v12, v47, v22, vcc
	s_nop 0
	v_cndmask_b32_e64 v9, 0, 1.0, s[54:55]
	v_add_f32_e32 v9, v9, v10
	v_or_b32_e32 v10, 6, v24
	v_cmp_eq_u32_e64 s[54:55], v10, v42
	v_cvt_pk_bf16_f32 v6, v8, v9
	s_nop 1
	v_cndmask_b32_e64 v10, 0, 1.0, s[54:55]
	v_add_f32_e32 v10, v10, v11
	v_or_b32_e32 v11, 7, v24
	v_cmp_eq_u32_e64 s[54:55], v11, v42
	s_nop 1
	v_cndmask_b32_e64 v11, 0, 1.0, s[54:55]
	v_add_f32_e32 v11, v11, v12
	v_cvt_pk_bf16_f32 v7, v10, v11
	ds_read_b128 v[16:19], v62 offset:8768
	ds_read_b128 v[20:23], v62 offset:8784
	s_waitcnt lgkmcnt(1)
	v_cvt_pk_bf16_f32 v16, v16, v17
	v_cvt_pk_bf16_f32 v17, v18, v19
	s_waitcnt lgkmcnt(0)
	v_cvt_pk_bf16_f32 v18, v20, v21
	v_or_b32_e32 v20, 16, v24
	v_cmp_eq_u32_e64 s[54:55], v20, v42
	v_cvt_pk_bf16_f32 v19, v22, v23
	s_nop 1
	v_cndmask_b32_e64 v20, 0, 1.0, s[54:55]
	v_cndmask_b32_e32 v21, v57, v30, vcc
	v_add_f32_e32 v20, v20, v21
	v_or_b32_e32 v21, 17, v24
	v_cmp_eq_u32_e64 s[54:55], v21, v42
	v_cndmask_b32_e32 v22, v59, v46, vcc
	v_cndmask_b32_e32 v23, v61, v48, vcc
	v_cndmask_b32_e64 v21, 0, 1.0, s[54:55]
	v_add_f32_e32 v21, v21, v22
	v_or_b32_e32 v22, 18, v24
	v_cmp_eq_u32_e64 s[54:55], v22, v42
	v_cndmask_b32_e32 v25, v60, v49, vcc
	v_mfma_f32_32x32x16_bf16 v[0:15], v[0:3], v[4:7], 0
	v_cndmask_b32_e64 v22, 0, 1.0, s[54:55]
	v_add_f32_e32 v22, v22, v23
	v_or_b32_e32 v23, 19, v24
	v_cmp_eq_u32_e64 s[54:55], v23, v42
	v_cndmask_b32_e32 v26, v58, v50, vcc
	v_cvt_pk_bf16_f32 v20, v20, v21
	s_nop 0
	v_cndmask_b32_e64 v23, 0, 1.0, s[54:55]
	v_add_f32_e32 v23, v23, v25
	v_or_b32_e32 v25, 20, v24
	v_cmp_eq_u32_e64 s[54:55], v25, v42
	v_cndmask_b32_e32 v27, v56, v51, vcc
	v_cndmask_b32_e32 v28, v55, v52, vcc
	v_cndmask_b32_e64 v25, 0, 1.0, s[54:55]
	v_add_f32_e32 v25, v25, v26
	v_or_b32_e32 v26, 21, v24
	v_cmp_eq_u32_e64 s[54:55], v26, v42
	v_cndmask_b32_e32 v29, v54, v53, vcc
	v_cvt_pk_bf16_f32 v21, v22, v23
	s_nop 0
	v_cndmask_b32_e64 v26, 0, 1.0, s[54:55]
	v_add_f32_e32 v26, v26, v27
	v_or_b32_e32 v27, 22, v24
	v_cmp_eq_u32_e64 s[54:55], v27, v42
	v_cvt_pk_bf16_f32 v22, v25, v26
	s_nop 1
	v_cndmask_b32_e64 v27, 0, 1.0, s[54:55]
	v_add_f32_e32 v27, v27, v28
	v_or_b32_e32 v28, 23, v24
	v_cmp_eq_u32_e32 vcc, v28, v42
	s_nop 1
	v_cndmask_b32_e64 v28, 0, 1.0, vcc
	v_add_f32_e32 v28, v28, v29
	v_cvt_pk_bf16_f32 v23, v27, v28
	s_nop 0
	v_mfma_f32_32x32x16_bf16 v[0:15], v[16:19], v[20:23], v[0:15]
